# prompt S5: f32-MFMA B*u for the next block software-pipelined under the recurrence and output tail; attention weight math hand-scheduled (both keys interleaved, dead range-scaling of log(1+e) removed)
# speedup vs baseline: 1.1301x; 1.0018x over previous
; __device__ __forceinline__ void s5_item(CPar p, int l, int s, int g, float* wl) {
;     ...
;     const float lr = p->in[I_LRE][gp], li = p->in[I_LIM][gp], step = expf(p->in[I_LSTEP][l * 32 + g]);
;     float sn, cs; sincos_red((double)li * (double)step, sn, cs);
;     const float mag = expf(lr * step), ab_re = mag * cs, ab_im = mag * sn;
;     const float den = lr * lr + li * li, nr = ab_re - 1.f, f_re = (nr * lr + ab_im * li) / den, f_im = (ab_im * lr - nr * li) / den;
;     float bbr[16], bbi[16];
; #pragma unroll
;     for (int hh = 0; hh < 16; ++hh) { const float br = p->in[I_BRE][(size_t)gp * 16 + hh], bi = p->in[I_BIM][(size_t)gp * 16 + hh]; bbr[hh] = f_re * br - f_im * bi; bbi[hh] = f_re * bi + f_im * br; }
.LBB0_679:
	s_or_b64 exec, exec, s[26:27]
	v_mul_f32_e32 v2, v62, v64
	v_mul_f32_e32 v3, 0x3fb8aa3b, v2
	s_mov_b32 s6, 0x3fb8aa3b
	v_fma_f32 v61, v2, s6, -v3
	v_rndne_f32_e32 v64, v3
	v_fmac_f32_e32 v61, 0x32a5705f, v2
	v_sub_f32_e32 v3, v3, v64
	v_add_f32_e32 v3, v3, v61
	v_exp_f32_e32 v3, v3
	v_cvt_i32_f32_e32 v61, v64
	s_mov_b32 s6, 0xc2ce8ed0
	v_cmp_ngt_f32_e32 vcc, s6, v2
	s_mov_b32 s6, 0x42b17218
	v_ldexp_f32 v3, v3, v61
	v_cndmask_b32_e32 v3, 0, v3, vcc
	v_cmp_nlt_f32_e32 vcc, s6, v2
	v_mov_b32_e32 v64, v63
	v_pk_mul_f32 v[66:67], v[62:63], v[62:63]
	v_cndmask_b32_e32 v3, v206, v3, vcc
	v_mul_f32_e32 v60, v3, v60
	v_fma_f32 v61, v3, v65, -1.0
	v_mul_f32_e32 v2, v3, v65
	v_pk_mul_f32 v[64:65], v[64:65], v[60:61] op_sel:[0,1] op_sel_hi:[0,0]
	v_pk_fma_f32 v[68:69], v[62:63], v[60:61], v[64:65] neg_lo:[0,0,1] neg_hi:[0,0,1]
	v_pk_fma_f32 v[62:63], v[62:63], v[60:61], v[64:65] op_sel_hi:[0,1,1]
	v_pk_add_f32 v[64:65], v[66:67], v[66:67] op_sel:[0,1] op_sel_hi:[0,1]
	v_div_scale_f32 v3, s[6:7], v65, v65, v63
	v_rcp_f32_e32 v61, v3
	v_lshlrev_b32_e32 v1, 3, v104
	v_mov_b32_e32 v106, 0
	v_lshlrev_b32_e32 v1, 1, v1
	v_fma_f32 v62, -v3, v61, 1.0
	v_fmac_f32_e32 v61, v62, v61
	v_div_scale_f32 v62, vcc, v63, v65, v63
	v_mul_f32_e32 v66, v62, v61
	v_fma_f32 v67, -v3, v66, v62
	v_fmac_f32_e32 v66, v67, v61
	v_fma_f32 v3, -v3, v66, v62
	v_div_fmas_f32 v3, v3, v61, v66
	v_div_fixup_f32 v101, v3, v65, v63
	v_div_scale_f32 v3, s[6:7], v64, v64, v68
	v_rcp_f32_e32 v61, v3
	s_lshl_b32 s11, s9, 11
	s_mov_b32 s12, 0
	v_mov_b32_e32 v107, v106
	v_fma_f32 v62, -v3, v61, 1.0
	v_fmac_f32_e32 v61, v62, v61
	v_div_scale_f32 v62, vcc, v68, v64, v68
	v_mul_f32_e32 v63, v62, v61
	v_fma_f32 v65, -v3, v63, v62
	v_fmac_f32_e32 v63, v65, v61
	v_fma_f32 v3, -v3, v63, v62
	v_div_fmas_f32 v3, v3, v61, v63
	v_div_fixup_f32 v100, v3, v64, v68
	v_pk_mul_f32 v[66:67], v[56:57], v[100:101]
	v_pk_mul_f32 v[62:63], v[100:101], v[56:57] op_sel:[1,0] op_sel_hi:[0,1]
	v_pk_fma_f32 v[56:57], v[100:101], v[52:53], v[62:63] neg_lo:[0,0,1] neg_hi:[0,0,1]
	v_pk_fma_f32 v[62:63], v[100:101], v[52:53], v[62:63]
	v_pk_fma_f32 v[64:65], v[52:53], v[100:101], v[66:67] op_sel:[1,0,1] op_sel_hi:[0,1,0] neg_lo:[0,0,1] neg_hi:[0,0,1]
	v_pk_fma_f32 v[52:53], v[52:53], v[100:101], v[66:67] op_sel:[1,0,1] op_sel_hi:[0,1,0]
	v_pk_mul_f32 v[70:71], v[100:101], v[58:59]
	v_pk_mul_f32 v[66:67], v[100:101], v[58:59] op_sel:[1,0] op_sel_hi:[0,1]
	v_pk_fma_f32 v[58:59], v[100:101], v[54:55], v[66:67] neg_lo:[0,0,1] neg_hi:[0,0,1]
	v_pk_fma_f32 v[66:67], v[100:101], v[54:55], v[66:67]
	v_pk_fma_f32 v[68:69], v[100:101], v[54:55], v[70:71] op_sel:[0,1,1] op_sel_hi:[1,0,0] neg_lo:[0,0,1] neg_hi:[0,0,1]
	v_pk_fma_f32 v[54:55], v[100:101], v[54:55], v[70:71] op_sel:[0,1,1] op_sel_hi:[1,0,0]
	v_pk_mul_f32 v[74:75], v[100:101], v[48:49]
	v_pk_mul_f32 v[70:71], v[100:101], v[48:49] op_sel:[1,0] op_sel_hi:[0,1]
	v_pk_fma_f32 v[48:49], v[100:101], v[44:45], v[70:71] neg_lo:[0,0,1] neg_hi:[0,0,1]
	v_pk_fma_f32 v[70:71], v[100:101], v[44:45], v[70:71]
	v_pk_fma_f32 v[72:73], v[100:101], v[44:45], v[74:75] op_sel:[0,1,1] op_sel_hi:[1,0,0] neg_lo:[0,0,1] neg_hi:[0,0,1]
	v_pk_fma_f32 v[44:45], v[100:101], v[44:45], v[74:75] op_sel:[0,1,1] op_sel_hi:[1,0,0]
	v_pk_mul_f32 v[78:79], v[100:101], v[50:51]
	v_pk_mul_f32 v[74:75], v[100:101], v[50:51] op_sel:[1,0] op_sel_hi:[0,1]
	v_pk_fma_f32 v[50:51], v[100:101], v[46:47], v[74:75] neg_lo:[0,0,1] neg_hi:[0,0,1]
	v_pk_fma_f32 v[74:75], v[100:101], v[46:47], v[74:75]
	v_pk_fma_f32 v[76:77], v[100:101], v[46:47], v[78:79] op_sel:[0,1,1] op_sel_hi:[1,0,0] neg_lo:[0,0,1] neg_hi:[0,0,1]
	v_pk_fma_f32 v[46:47], v[100:101], v[46:47], v[78:79] op_sel:[0,1,1] op_sel_hi:[1,0,0]
	v_pk_mul_f32 v[82:83], v[100:101], v[40:41]
	v_pk_mul_f32 v[78:79], v[100:101], v[40:41] op_sel:[1,0] op_sel_hi:[0,1]
	v_pk_fma_f32 v[40:41], v[100:101], v[36:37], v[78:79] neg_lo:[0,0,1] neg_hi:[0,0,1]
	v_pk_fma_f32 v[78:79], v[100:101], v[36:37], v[78:79]
	v_pk_fma_f32 v[80:81], v[100:101], v[36:37], v[82:83] op_sel:[0,1,1] op_sel_hi:[1,0,0] neg_lo:[0,0,1] neg_hi:[0,0,1]
	v_pk_fma_f32 v[36:37], v[100:101], v[36:37], v[82:83] op_sel:[0,1,1] op_sel_hi:[1,0,0]
	v_pk_mul_f32 v[86:87], v[100:101], v[42:43]
	v_pk_mul_f32 v[82:83], v[100:101], v[42:43] op_sel:[1,0] op_sel_hi:[0,1]
	v_pk_mul_f32 v[92:93], v[100:101], v[32:33]
	v_pk_mul_f32 v[32:33], v[100:101], v[32:33] op_sel:[1,0] op_sel_hi:[0,1]
	v_pk_fma_f32 v[42:43], v[100:101], v[38:39], v[82:83] neg_lo:[0,0,1] neg_hi:[0,0,1]
	v_pk_fma_f32 v[82:83], v[100:101], v[38:39], v[82:83]
	v_pk_fma_f32 v[84:85], v[100:101], v[38:39], v[86:87] op_sel:[0,1,1] op_sel_hi:[1,0,0] neg_lo:[0,0,1] neg_hi:[0,0,1]
	v_pk_fma_f32 v[38:39], v[100:101], v[38:39], v[86:87] op_sel:[0,1,1] op_sel_hi:[1,0,0]
	v_pk_fma_f32 v[86:87], v[100:101], v[28:29], v[32:33] neg_lo:[0,0,1] neg_hi:[0,0,1]
	v_pk_fma_f32 v[88:89], v[100:101], v[28:29], v[32:33]
	v_pk_fma_f32 v[90:91], v[100:101], v[28:29], v[92:93] op_sel:[0,1,1] op_sel_hi:[1,0,0] neg_lo:[0,0,1] neg_hi:[0,0,1]
	v_pk_fma_f32 v[92:93], v[100:101], v[28:29], v[92:93] op_sel:[0,1,1] op_sel_hi:[1,0,0]
	v_pk_mul_f32 v[28:29], v[100:101], v[34:35]
	v_pk_mul_f32 v[32:33], v[100:101], v[34:35] op_sel:[1,0] op_sel_hi:[0,1]
	v_pk_fma_f32 v[94:95], v[100:101], v[30:31], v[32:33] neg_lo:[0,0,1] neg_hi:[0,0,1]
	v_pk_fma_f32 v[96:97], v[100:101], v[30:31], v[32:33]
	v_pk_fma_f32 v[98:99], v[100:101], v[30:31], v[28:29] op_sel:[0,1,1] op_sel_hi:[1,0,0] neg_lo:[0,0,1] neg_hi:[0,0,1]
	v_pk_fma_f32 v[100:101], v[100:101], v[30:31], v[28:29] op_sel:[0,1,1] op_sel_hi:[1,0,0]
	v_lshlrev_b32_e32 v28, 1, v105
	v_mov_b32_e32 v29, v0
	v_lshl_add_u64 v[28:29], s[24:25], 0, v[28:29]
	v_lshlrev_b64 v[30:31], 1, v[102:103]
	v_lshl_add_u64 v[102:103], s[24:25], 0, v[30:31]
	v_mul_u32_u24_e32 v3, 0x110, v105
	v_lshlrev_b32_e32 v40, 2, v104
	v_lshl_add_u64 v[104:105], v[28:29], 0, v[30:31]
	s_waitcnt vmcnt(1)
; __device__ __forceinline__ unsigned pk2(float lo, float hi) { unsigned r; asm volatile("v_cvt_pk_bf16_f32 %0, %1, %2" : "=v"(r) : "v"(lo), "v"(hi)); return r; }
; __device__ __forceinline__ void s5_item(CPar p, int l, int s, int g, float* wl) {
;     ...
;     for (int hh = 0; hh < 16; ++hh) { const float br = p->in[I_BRE][(size_t)gp * 16 + hh], bi = p->in[I_BIM][(size_t)gp * 16 + hh]; bbr[hh] = f_re * br - f_im * bi; bbi[hh] = f_re * bi + f_im * br; }
;     bf16x8 cfrag[4];
; #pragma unroll
;     for (int ks = 0; ks < 4; ++ks) { const int k0 = ks * 32 + fq * 8; const bool im = k0 >= 64;
;         const float* cp = (im ? p->in[I_CIM] : p->in[I_CRE]) + ((size_t)(l * 32 + g) * 16 + fr) * 64 + (k0 & 63);
;         const f32x4 c0 = *(const f32x4*)cp, c1 = *(const f32x4*)(cp + 4); const float sg = im ? -1.f : 1.f;
;         u32x4 w; w[0] = pk2(sg * c0[0], sg * c0[1]); w[1] = pk2(sg * c0[2], sg * c0[3]); w[2] = pk2(sg * c1[0], sg * c1[1]); w[3] = pk2(sg * c1[2], sg * c1[3]);
;         cfrag[ks] = __builtin_bit_cast(bf16x8, w); }
;     float xr = prompt ? 0.f : p->in[I_S5R][(size_t)(l * 16 + b) * 2048 + g * 64 + lane], xi = prompt ? 0.f : p->in[I_S5I][(size_t)(l * 16 + b) * 2048 + g * 64 + lane];
;     const float dsk = p->in[I_DS5][(size_t)(l * 32 + g) * 16 + fr];
;     u32x4 ua = {0, 0, 0, 0}, ub = {0, 0, 0, 0};
;     { const int r0 = row_of(s, 0); if (lane < 16) { const u32x4* up = (const u32x4*)(U + (size_t)(r0 + lane) * 512 + g * 16); ua = up[0]; ub = up[1]; } }
;     for (int blk = 0; blk < nblk; ++blk) {
;         const int r0 = row_of(s, blk * 16);
;         const u32x4 ca = ua, cbv = ub;
;         if (blk + 1 < nblk && lane < 16) { const int r1 = row_of(s, blk * 16 + 16); const u32x4* up = (const u32x4*)(U + (size_t)(r1 + lane) * 512 + g * 16); ua = up[0]; ub = up[1]; }
	v_mov_b64_e32 v[30:31], v[22:23]
	s_waitcnt vmcnt(0)
	v_mov_b64_e32 v[34:35], v[26:27]
	v_mov_b32_e32 v63, v57
	v_mov_b32_e32 v53, v65
	v_mov_b32_e32 v67, v59
	v_mov_b32_e32 v55, v69
	v_mov_b32_e32 v71, v49
	v_mov_b32_e32 v45, v73
	v_mov_b32_e32 v75, v51
	v_mov_b32_e32 v47, v77
	v_mov_b32_e32 v79, v41
	v_mov_b32_e32 v37, v81
	v_mov_b32_e32 v83, v43
	v_mov_b32_e32 v39, v85
	v_mov_b32_e32 v89, v87
	v_mov_b32_e32 v93, v91
	v_mov_b32_e32 v97, v95
	v_mov_b32_e32 v101, v99
	v_add3_u32 v1, s52, v3, v1
	v_lshl_add_u32 v42, v108, 1, s52
	v_mov_b32_e32 v3, v2
	v_mov_b32_e32 v61, v60
	v_mov_b64_e32 v[28:29], v[20:21]
	v_mov_b64_e32 v[32:33], v[24:25]
	v_mov_b32_e32 v216, v62
	v_mov_b32_e32 v217, v65
	v_mov_b32_e32 v218, v52
	v_mov_b32_e32 v219, v57
	v_mov_b32_e32 v220, v66
	v_mov_b32_e32 v221, v69
	v_mov_b32_e32 v222, v54
	v_mov_b32_e32 v223, v59
	v_mov_b32_e32 v224, v70
	v_mov_b32_e32 v225, v73
	v_mov_b32_e32 v226, v44
	v_mov_b32_e32 v227, v49
	v_mov_b32_e32 v228, v74
	v_mov_b32_e32 v229, v77
	v_mov_b32_e32 v230, v46
	v_mov_b32_e32 v231, v51
	v_mov_b32_e32 v232, v78
	v_mov_b32_e32 v233, v81
	v_mov_b32_e32 v234, v36
	v_mov_b32_e32 v235, v41
	v_mov_b32_e32 v236, v82
	v_mov_b32_e32 v237, v85
	v_mov_b32_e32 v238, v38
	v_mov_b32_e32 v239, v43
	v_mov_b32_e32 v240, v88
	v_mov_b32_e32 v241, v91
	v_mov_b32_e32 v242, v92
	v_mov_b32_e32 v243, v87
	v_mov_b32_e32 v244, v96
	v_mov_b32_e32 v245, v99
	v_mov_b32_e32 v246, v100
	v_mov_b32_e32 v247, v95
	v_and_b32_e32 v198, 15, v108
	v_lshrrev_b32_e32 v199, 4, v108
	v_mul_u32_u24_e32 v180, 0x90, v108
	v_add_u32_e32 v180, s52, v180
	v_add_u32_e32 v180, 0x1200, v180
	ds_write_b128 v180, v[216:219]
	ds_write_b128 v180, v[220:223] offset:16
	ds_write_b128 v180, v[224:227] offset:32
	ds_write_b128 v180, v[228:231] offset:48
	ds_write_b128 v180, v[232:235] offset:64
	ds_write_b128 v180, v[236:239] offset:80
	ds_write_b128 v180, v[240:243] offset:96
	ds_write_b128 v180, v[244:247] offset:112
	v_mul_u32_u24_e32 v181, 0x90, v198
	v_lshl_add_u32 v181, v199, 5, v181
	v_add_u32_e32 v181, s52, v181
	v_add_u32_e32 v181, 0x1200, v181
	s_waitcnt lgkmcnt(0)
	ds_read_b128 v[216:219], v181
	ds_read_b128 v[220:223], v181 offset:16
	ds_read_b128 v[224:227], v181 offset:2304
	ds_read_b128 v[228:231], v181 offset:2320
	ds_read_b128 v[232:235], v181 offset:4608
	ds_read_b128 v[236:239], v181 offset:4624
	ds_read_b128 v[240:243], v181 offset:6912
	ds_read_b128 v[244:247], v181 offset:6928
	v_lshlrev_b32_e32 v182, 3, v199
	v_mov_b32_e32 v183, 0
	v_lshl_add_u64 v[184:185], v[102:103], 0, v[182:183]
	v_mul_u32_u24_e32 v190, 0x50, v198
	v_lshl_add_u32 v190, v199, 4, v190
	v_add_u32_e32 v190, s52, v190
	v_add_u32_e32 v190, 0x1200, v190
	v_mul_u32_u24_e32 v191, 0x50, v108
	v_add_u32_e32 v191, s52, v191
	v_add_u32_e32 v191, 0x1200, v191
	v_or_b32_e32 v180, s10, v198
	v_mov_b32_e32 v181, 0
	v_lshlrev_b64 v[180:181], 10, v[180:181]
	v_lshl_add_u64 v[180:181], v[184:185], 0, v[180:181]
	global_load_dwordx2 v[186:187], v[180:181], off
	s_waitcnt vmcnt(0) lgkmcnt(0)
	v_add_u32_e32 v180, s11, v198
	v_mov_b32_e32 v181, 0
	v_lshlrev_b64 v[180:181], 10, v[180:181]
	v_lshl_add_u64 v[180:181], v[184:185], 0, v[180:181]
	global_load_dwordx2 v[188:189], v[180:181], off
	v_lshlrev_b32_e32 v176, 16, v186
	v_and_b32_e32 v177, 0xffff0000, v186
	v_lshlrev_b32_e32 v178, 16, v187
	v_and_b32_e32 v179, 0xffff0000, v187
	v_mfma_f32_16x16x4_f32 v[124:127], v176, v216, 0
	v_mfma_f32_16x16x4_f32 v[128:131], v176, v217, 0
	v_mfma_f32_16x16x4_f32 v[132:135], v176, v224, 0
	v_mfma_f32_16x16x4_f32 v[140:143], v176, v225, 0
	v_mfma_f32_16x16x4_f32 v[144:147], v176, v232, 0
	v_mfma_f32_16x16x4_f32 v[148:151], v176, v233, 0
	v_mfma_f32_16x16x4_f32 v[152:155], v176, v240, 0
	v_mfma_f32_16x16x4_f32 v[248:251], v176, v241, 0
	v_mfma_f32_16x16x4_f32 v[124:127], v177, v218, v[124:127]
	v_mfma_f32_16x16x4_f32 v[128:131], v177, v219, v[128:131]
	v_mfma_f32_16x16x4_f32 v[132:135], v177, v226, v[132:135]
	v_mfma_f32_16x16x4_f32 v[140:143], v177, v227, v[140:143]
	v_mfma_f32_16x16x4_f32 v[144:147], v177, v234, v[144:147]
	v_mfma_f32_16x16x4_f32 v[148:151], v177, v235, v[148:151]
	v_mfma_f32_16x16x4_f32 v[152:155], v177, v242, v[152:155]
	v_mfma_f32_16x16x4_f32 v[248:251], v177, v243, v[248:251]
	v_mfma_f32_16x16x4_f32 v[124:127], v178, v220, v[124:127]
	v_mfma_f32_16x16x4_f32 v[128:131], v178, v221, v[128:131]
	v_mfma_f32_16x16x4_f32 v[132:135], v178, v228, v[132:135]
	v_mfma_f32_16x16x4_f32 v[140:143], v178, v229, v[140:143]
	v_mfma_f32_16x16x4_f32 v[144:147], v178, v236, v[144:147]
	v_mfma_f32_16x16x4_f32 v[148:151], v178, v237, v[148:151]
	v_mfma_f32_16x16x4_f32 v[152:155], v178, v244, v[152:155]
	v_mfma_f32_16x16x4_f32 v[248:251], v178, v245, v[248:251]
	v_mfma_f32_16x16x4_f32 v[124:127], v179, v222, v[124:127]
	v_mfma_f32_16x16x4_f32 v[128:131], v179, v223, v[128:131]
	v_mfma_f32_16x16x4_f32 v[132:135], v179, v230, v[132:135]
	v_mfma_f32_16x16x4_f32 v[140:143], v179, v231, v[140:143]
	v_mfma_f32_16x16x4_f32 v[144:147], v179, v238, v[144:147]
	v_mfma_f32_16x16x4_f32 v[148:151], v179, v239, v[148:151]
	v_mfma_f32_16x16x4_f32 v[152:155], v179, v246, v[152:155]
	v_mfma_f32_16x16x4_f32 v[248:251], v179, v247, v[248:251]
	s_nop 7
	s_nop 1
	ds_write_b128 v190, v[124:127]
	ds_write_b128 v190, v[128:131] offset:5120
	ds_write_b128 v190, v[132:135] offset:1280
	ds_write_b128 v190, v[140:143] offset:6400
	ds_write_b128 v190, v[144:147] offset:2560
	ds_write_b128 v190, v[148:151] offset:7680
	ds_write_b128 v190, v[152:155] offset:3840
	ds_write_b128 v190, v[248:251] offset:8960
	s_waitcnt lgkmcnt(0)
	ds_read_b128 v[64:67], v191
	ds_read_b128 v[68:71], v191 offset:16
	ds_read_b128 v[72:75], v191 offset:32
	ds_read_b128 v[76:79], v191 offset:48
	ds_read_b128 v[80:83], v191 offset:5120
	ds_read_b128 v[84:87], v191 offset:5136
	ds_read_b128 v[88:91], v191 offset:5152
	ds_read_b128 v[92:95], v191 offset:5168
	s_waitcnt lgkmcnt(0)
	s_waitcnt vmcnt(0)
	v_mov_b64_e32 v[186:187], v[188:189]
	s_branch .LBB0_681
; __device__ __forceinline__ float lo_f(unsigned w) { return __uint_as_float(w << 16); }
; __device__ __forceinline__ float hi_f(unsigned w) { return __uint_as_float(w & 0xffff0000u); }
; __device__ __forceinline__ bf16_t f2bf_(float v) { return (bf16_t)(pk2(v, v) & 0xffffu); }
; __device__ __forceinline__ void s5_item(CPar p, int l, int s, int g, float* wl) {
;     ...
;     for (int blk = 0; blk < nblk; ++blk) {
;         const int r0 = row_of(s, blk * 16);
;         const u32x4 ca = ua, cbv = ub;
;         if (blk + 1 < nblk && lane < 16) { const int r1 = row_of(s, blk * 16 + 16); const u32x4* up = (const u32x4*)(U + (size_t)(r1 + lane) * 512 + g * 16); ua = up[0]; ub = up[1]; }
; #pragma unroll
;         for (int i = 0; i < 16; ++i) {
;             float br4[4] = {0.f, 0.f, 0.f, 0.f}, bi4[4] = {0.f, 0.f, 0.f, 0.f};
; #pragma unroll
;             for (int w = 0; w < 8; ++w) { const unsigned word = (unsigned)__builtin_amdgcn_readlane((int)(w < 4 ? ca[w] : cbv[w - 4]), i);
;                 const float u0 = lo_f(word), u1 = hi_f(word);
;                 br4[w & 3] += bbr[2 * w] * u0 + bbr[2 * w + 1] * u1; bi4[w & 3] += bbi[2 * w] * u0 + bbi[2 * w + 1] * u1; }
;             const float bur = (br4[0] + br4[1]) + (br4[2] + br4[3]), bui = (bi4[0] + bi4[1]) + (bi4[2] + bi4[3]);
;             const float nxr = ab_re * xr - ab_im * xi + bur, nxi = ab_re * xi + ab_im * xr + bui; xr = nxr; xi = nxi;
;             Xb[i * LBX + lane] = f2bf_(xr); Xb[i * LBX + 64 + lane] = f2bf_(xi);
.LBB0_680:
	s_or_b64 exec, exec, s[24:25]
	s_add_i32 s6, s11, -16
	s_cmp_eq_u32 s12, 0
	s_cselect_b32 s13, s10, s6
	v_or_b32_e32 v192, s13, v40
	v_ashrrev_i32_e32 v193, 31, v192
	v_lshlrev_b64 v[192:193], 10, v[192:193]
	v_lshl_add_u64 v[192:193], v[104:105], 0, v[192:193]
	global_load_ushort v194, v[192:193], off
	global_load_ushort v195, v[192:193], off offset:1024
	global_load_ushort v196, v[192:193], off offset:2048
	global_load_ushort v197, v[192:193], off offset:3072
	v_add_u32_e32 v180, s11, v198
	v_add_u32_e32 v180, 16, v180
	v_mov_b32_e32 v181, 0
	v_lshlrev_b64 v[180:181], 10, v[180:181]
	v_lshl_add_u64 v[180:181], v[184:185], 0, v[180:181]
	global_load_dwordx2 v[188:189], v[180:181], off
	v_lshlrev_b32_e32 v176, 16, v186
	v_and_b32_e32 v177, 0xffff0000, v186
	v_lshlrev_b32_e32 v178, 16, v187
	v_and_b32_e32 v179, 0xffff0000, v187
	v_mfma_f32_16x16x4_f32 v[124:127], v176, v216, 0
	v_fma_f32 v180, v2, v107, v80
	v_fma_f32 v181, v2, v106, v64
	v_fma_f32 v180, -v60, v106, v180
	v_fma_f32 v106, v60, v107, v181
	v_mov_b32_e32 v107, v180
	v_cvt_pk_bf16_f32 v182, v107, v107
	ds_write_b16 v42, v182
	v_cvt_pk_bf16_f32 v183, v106, v106
	ds_write_b16 v42, v183 offset:128
	v_mfma_f32_16x16x4_f32 v[128:131], v176, v217, 0
	v_fma_f32 v180, v2, v107, v81
	v_fma_f32 v181, v2, v106, v65
	v_fma_f32 v180, -v60, v106, v180
	v_fma_f32 v106, v60, v107, v181
	v_mov_b32_e32 v107, v180
	v_cvt_pk_bf16_f32 v182, v107, v107
	ds_write_b16 v42, v182 offset:272
	v_cvt_pk_bf16_f32 v183, v106, v106
	ds_write_b16 v42, v183 offset:400
	v_mfma_f32_16x16x4_f32 v[132:135], v176, v224, 0
	v_fma_f32 v180, v2, v107, v82
	v_fma_f32 v181, v2, v106, v66
	v_fma_f32 v180, -v60, v106, v180
	v_fma_f32 v106, v60, v107, v181
	v_mov_b32_e32 v107, v180
	v_cvt_pk_bf16_f32 v182, v107, v107
	ds_write_b16 v42, v182 offset:544
	v_cvt_pk_bf16_f32 v183, v106, v106
	ds_write_b16 v42, v183 offset:672
	v_mfma_f32_16x16x4_f32 v[140:143], v176, v225, 0
	v_fma_f32 v180, v2, v107, v83
	v_fma_f32 v181, v2, v106, v67
	v_fma_f32 v180, -v60, v106, v180
	v_fma_f32 v106, v60, v107, v181
	v_mov_b32_e32 v107, v180
	v_cvt_pk_bf16_f32 v182, v107, v107
	ds_write_b16 v42, v182 offset:816
	v_cvt_pk_bf16_f32 v183, v106, v106
	ds_write_b16 v42, v183 offset:944
	v_mfma_f32_16x16x4_f32 v[144:147], v176, v232, 0
	v_fma_f32 v180, v2, v107, v84
	v_fma_f32 v181, v2, v106, v68
	v_fma_f32 v180, -v60, v106, v180
	v_fma_f32 v106, v60, v107, v181
	v_mov_b32_e32 v107, v180
	v_cvt_pk_bf16_f32 v182, v107, v107
	ds_write_b16 v42, v182 offset:1088
	v_cvt_pk_bf16_f32 v183, v106, v106
	ds_write_b16 v42, v183 offset:1216
	v_mfma_f32_16x16x4_f32 v[148:151], v176, v233, 0
	v_fma_f32 v180, v2, v107, v85
	v_fma_f32 v181, v2, v106, v69
	v_fma_f32 v180, -v60, v106, v180
	v_fma_f32 v106, v60, v107, v181
	v_mov_b32_e32 v107, v180
	v_cvt_pk_bf16_f32 v182, v107, v107
	ds_write_b16 v42, v182 offset:1360
	v_cvt_pk_bf16_f32 v183, v106, v106
	ds_write_b16 v42, v183 offset:1488
	v_mfma_f32_16x16x4_f32 v[152:155], v176, v240, 0
	v_fma_f32 v180, v2, v107, v86
	v_fma_f32 v181, v2, v106, v70
	v_fma_f32 v180, -v60, v106, v180
	v_fma_f32 v106, v60, v107, v181
	v_mov_b32_e32 v107, v180
	v_cvt_pk_bf16_f32 v182, v107, v107
	ds_write_b16 v42, v182 offset:1632
	v_cvt_pk_bf16_f32 v183, v106, v106
	ds_write_b16 v42, v183 offset:1760
	v_mfma_f32_16x16x4_f32 v[248:251], v176, v241, 0
	v_fma_f32 v180, v2, v107, v87
	v_fma_f32 v181, v2, v106, v71
	v_fma_f32 v180, -v60, v106, v180
	v_fma_f32 v106, v60, v107, v181
	v_mov_b32_e32 v107, v180
	v_cvt_pk_bf16_f32 v182, v107, v107
	ds_write_b16 v42, v182 offset:1904
	v_cvt_pk_bf16_f32 v183, v106, v106
	ds_write_b16 v42, v183 offset:2032
	v_mfma_f32_16x16x4_f32 v[124:127], v177, v218, v[124:127]
	v_fma_f32 v180, v2, v107, v88
	v_fma_f32 v181, v2, v106, v72
	v_fma_f32 v180, -v60, v106, v180
	v_fma_f32 v106, v60, v107, v181
	v_mov_b32_e32 v107, v180
	v_cvt_pk_bf16_f32 v182, v107, v107
	ds_write_b16 v42, v182 offset:2176
	v_cvt_pk_bf16_f32 v183, v106, v106
	ds_write_b16 v42, v183 offset:2304
	v_mfma_f32_16x16x4_f32 v[128:131], v177, v219, v[128:131]
	v_fma_f32 v180, v2, v107, v89
	v_fma_f32 v181, v2, v106, v73
	v_fma_f32 v180, -v60, v106, v180
	v_fma_f32 v106, v60, v107, v181
	v_mov_b32_e32 v107, v180
	v_cvt_pk_bf16_f32 v182, v107, v107
	ds_write_b16 v42, v182 offset:2448
	v_cvt_pk_bf16_f32 v183, v106, v106
	ds_write_b16 v42, v183 offset:2576
	v_mfma_f32_16x16x4_f32 v[132:135], v177, v226, v[132:135]
	v_fma_f32 v180, v2, v107, v90
	v_fma_f32 v181, v2, v106, v74
	v_fma_f32 v180, -v60, v106, v180
	v_fma_f32 v106, v60, v107, v181
	v_mov_b32_e32 v107, v180
	v_cvt_pk_bf16_f32 v182, v107, v107
	ds_write_b16 v42, v182 offset:2720
	v_cvt_pk_bf16_f32 v183, v106, v106
	ds_write_b16 v42, v183 offset:2848
	v_mfma_f32_16x16x4_f32 v[140:143], v177, v227, v[140:143]
	v_fma_f32 v180, v2, v107, v91
	v_fma_f32 v181, v2, v106, v75
	v_fma_f32 v180, -v60, v106, v180
	v_fma_f32 v106, v60, v107, v181
	v_mov_b32_e32 v107, v180
	v_cvt_pk_bf16_f32 v182, v107, v107
	ds_write_b16 v42, v182 offset:2992
	v_cvt_pk_bf16_f32 v183, v106, v106
	ds_write_b16 v42, v183 offset:3120
	v_mfma_f32_16x16x4_f32 v[144:147], v177, v234, v[144:147]
	v_fma_f32 v180, v2, v107, v92
	v_fma_f32 v181, v2, v106, v76
	v_fma_f32 v180, -v60, v106, v180
	v_fma_f32 v106, v60, v107, v181
	v_mov_b32_e32 v107, v180
	v_cvt_pk_bf16_f32 v182, v107, v107
	ds_write_b16 v42, v182 offset:3264
	v_cvt_pk_bf16_f32 v183, v106, v106
	ds_write_b16 v42, v183 offset:3392
	v_mfma_f32_16x16x4_f32 v[148:151], v177, v235, v[148:151]
	v_fma_f32 v180, v2, v107, v93
	v_fma_f32 v181, v2, v106, v77
	v_fma_f32 v180, -v60, v106, v180
	v_fma_f32 v106, v60, v107, v181
	v_mov_b32_e32 v107, v180
	v_cvt_pk_bf16_f32 v182, v107, v107
	ds_write_b16 v42, v182 offset:3536
	v_cvt_pk_bf16_f32 v183, v106, v106
	ds_write_b16 v42, v183 offset:3664
	v_mfma_f32_16x16x4_f32 v[152:155], v177, v242, v[152:155]
	v_fma_f32 v180, v2, v107, v94
	v_fma_f32 v181, v2, v106, v78
	v_fma_f32 v180, -v60, v106, v180
	v_fma_f32 v106, v60, v107, v181
	v_mov_b32_e32 v107, v180
	v_cvt_pk_bf16_f32 v182, v107, v107
	ds_write_b16 v42, v182 offset:3808
	v_cvt_pk_bf16_f32 v183, v106, v106
	ds_write_b16 v42, v183 offset:3936
	v_mfma_f32_16x16x4_f32 v[248:251], v177, v243, v[248:251]
	v_fma_f32 v180, v2, v107, v95
	v_fma_f32 v181, v2, v106, v79
	v_fma_f32 v180, -v60, v106, v180
	v_fma_f32 v106, v60, v107, v181
	v_mov_b32_e32 v107, v180
	v_cvt_pk_bf16_f32 v182, v107, v107
	ds_write_b16 v42, v182 offset:4080
	v_cvt_pk_bf16_f32 v183, v106, v106
	ds_write_b16 v42, v183 offset:4208
	s_add_i32 s12, s12, 1
	s_add_i32 s11, s11, 16
	s_cmpk_eq_i32 s12, 0x81
	s_waitcnt lgkmcnt(0)
; __device__ __forceinline__ float bf2f(bf16_t v) { return __uint_as_float((unsigned)v << 16); }
; __device__ __forceinline__ float geluf_(float y) { const float a = 0.7978845608f * (y + 0.044715f * y * y * y); const float t = __expf(2.f * a); return 0.5f * y * (2.f - 2.f * __builtin_amdgcn_rcpf(t + 1.f)); }
; __device__ __forceinline__ bf16_t f2bf_(float v) { return (bf16_t)(pk2(v, v) & 0xffffu); }
; __device__ __forceinline__ void s5_item(CPar p, int l, int s, int g, float* wl) {
;     ...
;         __builtin_amdgcn_wave_barrier(); asm volatile("s_waitcnt lgkmcnt(0)" ::: "memory");
;         f32x4 y = {0.f, 0.f, 0.f, 0.f};
; #pragma unroll
;         for (int ks = 0; ks < 4; ++ks) y = __builtin_amdgcn_mfma_f32_16x16x32_bf16(*(const bf16x8*)(Xb + fr * LBX + ks * 32 + fq * 8), cfrag[ks], y, 0, 0, 0);
; #pragma unroll
;         for (int r = 0; r < 4; ++r) { bf16_t* up = U + (size_t)(r0 + fq * 4 + r) * 512 + g * 16 + fr; *up = f2bf_(geluf_(y[r] + dsk * bf2f(*up))); }
;         __builtin_amdgcn_wave_barrier(); asm volatile("s_waitcnt lgkmcnt(0)" ::: "memory");
	ds_read_b128 v[20:23], v1
	ds_read_b128 v[24:27], v1 offset:64
	v_mfma_f32_16x16x4_f32 v[124:127], v178, v220, v[124:127]
	s_waitcnt lgkmcnt(1)
	v_mfma_f32_16x16x32_bf16 v[20:23], v[20:23], v[4:7], 0
	s_waitcnt lgkmcnt(0)
	v_mfma_f32_16x16x32_bf16 v[20:23], v[24:27], v[8:11], v[20:23]
	ds_read_b128 v[24:27], v1 offset:128
	ds_read_b128 v[110:113], v1 offset:192
	v_mfma_f32_16x16x4_f32 v[128:131], v178, v221, v[128:131]
	s_waitcnt lgkmcnt(1)
	v_mfma_f32_16x16x32_bf16 v[20:23], v[24:27], v[12:15], v[20:23]
	v_or_b32_e32 v24, s13, v40
	v_ashrrev_i32_e32 v25, 31, v24
	v_lshlrev_b64 v[26:27], 10, v[24:25]
	v_lshl_add_u64 v[26:27], v[104:105], 0, v[26:27]
	v_mfma_f32_16x16x4_f32 v[132:135], v178, v228, v[132:135]
	s_waitcnt lgkmcnt(0)
	v_mfma_f32_16x16x32_bf16 v[20:23], v[110:113], v[16:19], v[20:23]
	v_or_b32_e32 v110, 1, v24
	v_ashrrev_i32_e32 v111, 31, v110
	v_lshlrev_b64 v[110:111], 10, v[110:111]
	v_mfma_f32_16x16x4_f32 v[140:143], v178, v229, v[140:143]
	v_lshl_add_u64 v[110:111], v[104:105], 0, v[110:111]
	s_waitcnt vmcnt(0)
	v_lshlrev_b32_e32 v25, 16, v194
	s_nop 1
	v_fma_f32 v20, v109, v25, v20
	v_mul_f32_e32 v25, 0x3d372713, v20
	v_mfma_f32_16x16x4_f32 v[144:147], v178, v236, v[144:147]
	v_mul_f32_e32 v25, v20, v25
	v_fma_f32 v25, v20, v25, v20
	v_mul_f32_e32 v25, 0x3f4c422a, v25
	v_add_f32_e32 v25, v25, v25
	v_mul_f32_e32 v25, 0x3fb8aa3b, v25
	v_exp_f32_e32 v25, v25
	v_mfma_f32_16x16x4_f32 v[148:151], v178, v237, v[148:151]
	v_mul_f32_e32 v20, 0.5, v20
	v_add_f32_e32 v25, 1.0, v25
	v_rcp_f32_e32 v25, v25
	s_nop 0
	v_fma_f32 v25, v25, -2.0, 2.0
	v_mul_f32_e32 v20, v20, v25
	v_mfma_f32_16x16x4_f32 v[152:155], v178, v244, v[152:155]
	v_cvt_pk_bf16_f32 v20, v20, v20
	v_lshlrev_b32_e32 v25, 16, v195
	v_fma_f32 v21, v109, v25, v21
	v_mul_f32_e32 v25, 0x3d372713, v21
	v_mfma_f32_16x16x4_f32 v[248:251], v178, v245, v[248:251]
	v_mul_f32_e32 v25, v21, v25
	v_fma_f32 v25, v21, v25, v21
	v_mul_f32_e32 v25, 0x3f4c422a, v25
	v_add_f32_e32 v25, v25, v25
	v_mul_f32_e32 v25, 0x3fb8aa3b, v25
	v_exp_f32_e32 v25, v25
	v_mfma_f32_16x16x4_f32 v[124:127], v179, v222, v[124:127]
	global_store_short v[26:27], v20, off
	v_mul_f32_e32 v20, 0.5, v21
	v_add_f32_e32 v25, 1.0, v25
	v_rcp_f32_e32 v25, v25
	s_nop 0
	v_fma_f32 v21, v25, -2.0, 2.0
	v_mfma_f32_16x16x4_f32 v[128:131], v179, v223, v[128:131]
	v_mul_f32_e32 v20, v20, v21
	v_cvt_pk_bf16_f32 v25, v20, v20
	v_or_b32_e32 v20, 2, v24
	v_ashrrev_i32_e32 v21, 31, v20
	v_lshlrev_b64 v[20:21], 10, v[20:21]
	v_lshl_add_u64 v[20:21], v[104:105], 0, v[20:21]
	v_mfma_f32_16x16x4_f32 v[132:135], v179, v230, v[132:135]
	v_or_b32_e32 v24, 3, v24
	global_store_short v[110:111], v25, off
	v_lshlrev_b32_e32 v26, 16, v196
	v_fma_f32 v22, v109, v26, v22
	v_mfma_f32_16x16x4_f32 v[140:143], v179, v231, v[140:143]
	v_mul_f32_e32 v26, 0x3d372713, v22
	v_mul_f32_e32 v26, v22, v26
	v_fma_f32 v26, v22, v26, v22
	v_mul_f32_e32 v26, 0x3f4c422a, v26
	v_add_f32_e32 v26, v26, v26
	v_mul_f32_e32 v26, 0x3fb8aa3b, v26
	v_mfma_f32_16x16x4_f32 v[144:147], v179, v238, v[144:147]
	v_exp_f32_e32 v26, v26
	v_mul_f32_e32 v22, 0.5, v22
	v_add_f32_e32 v26, 1.0, v26
	v_rcp_f32_e32 v26, v26
	s_nop 0
	v_fma_f32 v25, v26, -2.0, 2.0
	v_mfma_f32_16x16x4_f32 v[148:151], v179, v239, v[148:151]
	v_mul_f32_e32 v22, v22, v25
	v_ashrrev_i32_e32 v25, 31, v24
	v_lshlrev_b64 v[24:25], 10, v[24:25]
	v_lshl_add_u64 v[24:25], v[104:105], 0, v[24:25]
	v_cvt_pk_bf16_f32 v22, v22, v22
	v_mfma_f32_16x16x4_f32 v[152:155], v179, v246, v[152:155]
	v_lshlrev_b32_e32 v26, 16, v197
	v_fmac_f32_e32 v23, v109, v26
	v_mul_f32_e32 v26, 0x3d372713, v23
	v_mul_f32_e32 v26, v23, v26
	v_fma_f32 v26, v23, v26, v23
	v_mfma_f32_16x16x4_f32 v[248:251], v179, v247, v[248:251]
	v_mul_f32_e32 v26, 0x3f4c422a, v26
	v_add_f32_e32 v26, v26, v26
	v_mul_f32_e32 v26, 0x3fb8aa3b, v26
	v_exp_f32_e32 v26, v26
	global_store_short v[20:21], v22, off
	v_mul_f32_e32 v20, 0.5, v23
	v_add_f32_e32 v26, 1.0, v26
	v_rcp_f32_e32 v26, v26
	s_nop 0
	v_fma_f32 v21, v26, -2.0, 2.0
	v_mul_f32_e32 v20, v20, v21
	v_cvt_pk_bf16_f32 v20, v20, v20
	global_store_short v[24:25], v20, off
	s_waitcnt lgkmcnt(0)
	s_nop 7
	s_nop 1
	ds_write_b128 v190, v[124:127]
	ds_write_b128 v190, v[128:131] offset:5120
	ds_write_b128 v190, v[132:135] offset:1280
	ds_write_b128 v190, v[140:143] offset:6400
	ds_write_b128 v190, v[144:147] offset:2560
	ds_write_b128 v190, v[148:151] offset:7680
	ds_write_b128 v190, v[152:155] offset:3840
	ds_write_b128 v190, v[248:251] offset:8960
	s_waitcnt lgkmcnt(0)
	ds_read_b128 v[64:67], v191
	ds_read_b128 v[68:71], v191 offset:16
	ds_read_b128 v[72:75], v191 offset:32
	ds_read_b128 v[76:79], v191 offset:48
	ds_read_b128 v[80:83], v191 offset:5120
	ds_read_b128 v[84:87], v191 offset:5136
	ds_read_b128 v[88:91], v191 offset:5152
	ds_read_b128 v[92:95], v191 offset:5168
	s_waitcnt lgkmcnt(0)
	v_mov_b64_e32 v[186:187], v[188:189]
	v_mov_b64_e32 v[24:25], v[32:33]
	v_mov_b64_e32 v[20:21], v[28:29]
	v_mov_b64_e32 v[26:27], v[34:35]
	v_mov_b64_e32 v[22:23], v[30:31]
	s_cbranch_scc1 .LBB0_668

; __device__ __forceinline__ unsigned pk2(float lo, float hi) { unsigned r; asm volatile("v_cvt_pk_bf16_f32 %0, %1, %2" : "=v"(r) : "v"(lo), "v"(hi)); return r; }
; __device__ __forceinline__ float dot2bf(unsigned a, unsigned b, float c) { return __builtin_amdgcn_fdot2_f32_bf16(__builtin_bit_cast(bf2_t, a), __builtin_bit_cast(bf2_t, b), c, false); }
; __device__ __forceinline__ void attn_item(CPar p, int l, int item, float* wl) {
;     ...
;             const bool v0 = active && (j0 < nh + i), v1 = active && (j1 >= 0) && (j1 < nh + i);
;             const float e0 = __expf(-z0), ls0 = -__logf(1.f + e0);
;             const float w0 = v0 ? __expf(ls0 + run) : 0.f; run += v0 ? (ls0 - z0) : 0.f;
;             const float e1 = __expf(-z1), ls1 = -__logf(1.f + e1);
;             const float w1 = v1 ? __expf(ls1 + run) : 0.f; run += v1 ? (ls1 - z1) : 0.f;
;             const unsigned wp = pk2(w0, w1);
; #pragma unroll
;             for (int d4 = 0; d4 < 16; ++d4) { const u32x4 vv = *(const u32x4*)(Vp + m * 64 + d4 * 4);
; #pragma unroll
;                 for (int c = 0; c < 4; ++c) o[d4 * 4 + c] = dot2bf(wp, vv[c], o[d4 * 4 + c]); } }
.LBB0_771:
	ds_read_b64 v[252:253], v250
	v_add_u32_e32 v250, 8, v250
	v_cmp_lt_i32_e32 vcc, s1, v184
	s_and_b64 vcc, s[40:41], vcc
	s_cmp_gt_i32 s1, 0
	s_cselect_b64 s[6:7], -1, 0
	s_and_b64 s[6:7], s[40:41], s[6:7]
	v_cmp_le_i32_e64 s[44:45], s1, v184
	s_addk_i32 s9, 0x100
	s_add_i32 s1, s1, -2
	s_waitcnt lgkmcnt(0)
	v_mul_f32_e32 v212, 0xbfb8aa3b, v252
	v_mul_f32_e32 v213, 0xbfb8aa3b, v253
	v_exp_f32_e32 v212, v212
	v_exp_f32_e32 v213, v213
	s_and_b64 s[44:45], s[6:7], s[44:45]
	v_add_f32_e32 v212, 1.0, v212
	v_add_f32_e32 v213, 1.0, v213
	v_log_f32_e32 v212, v212
	v_log_f32_e32 v213, v213
	v_mul_f32_e32 v3, 0x3f317217, v212
	v_mul_f32_e32 v79, 0x3f317217, v213
	v_fma_f32 v3, v212, s90, -v3
	v_fma_f32 v79, v213, s90, -v79
	v_fmac_f32_e32 v3, 0x3377d1cf, v212
	v_fmac_f32_e32 v79, 0x3377d1cf, v213
	v_fmac_f32_e32 v3, 0x3f317217, v212
	v_fmac_f32_e32 v79, 0x3f317217, v213
	v_cmp_lt_f32_e64 s[46:47], |v212|, s23
	v_cmp_lt_f32_e64 s[48:49], |v213|, s23
	s_nop 0
	v_cndmask_b32_e64 v212, v212, v3, s[46:47]
	v_cndmask_b32_e64 v213, v213, v79, s[48:49]
	v_sub_f32_e32 v3, v224, v212
	v_sub_f32_e64 v79, -v212, v252
	v_mul_f32_e32 v3, 0x3fb8aa3b, v3
	v_cndmask_b32_e32 v79, 0, v79, vcc
	v_exp_f32_e32 v3, v3
	v_add_f32_e32 v79, v224, v79
	v_sub_f32_e32 v212, v79, v213
	v_sub_f32_e64 v213, -v213, v253
	v_mul_f32_e32 v212, 0x3fb8aa3b, v212
	v_cndmask_b32_e32 v3, 0, v3, vcc
	v_exp_f32_e32 v212, v212
	v_cndmask_b32_e64 v213, 0, v213, s[44:45]
	v_add_co_u32_e32 v1, vcc, 1, v1
	v_add_f32_e32 v224, v79, v213
	v_cndmask_b32_e64 v212, 0, v212, s[44:45]
	v_cvt_pk_bf16_f32 v212, v3, v212
	s_and_b64 vcc, exec, vcc
	ds_write_b32 v251, v212
	v_add_u32_e32 v251, 4, v251
	s_cbranch_vccz .LBB0_771
	s_mov_b32 s1, 0xc2480000
	v_cmp_gt_f32_e32 vcc, s1, v224
	s_or_b64 s[6:7], s[42:43], vcc
	s_waitcnt lgkmcnt(0)
	v_mbcnt_lo_u32_b32 v250, -1, 0
	v_mbcnt_hi_u32_b32 v250, -1, v250
	v_and_b32_e32 v251, 15, v250
	v_lshrrev_b32_e32 v252, 4, v250
	v_lshlrev_b32_e32 v253, 2, v251
	v_lshl_add_u32 v253, v252, 10, v253
	v_add_u32_e32 v253, s52, v253
	v_add_u32_e32 v253, 0x1000, v253
	v_mul_u32_u24_e32 v251, 0x90, v251
	v_lshl_add_u32 v251, v252, 4, v251
	v_add_u32_e32 v251, s52, v251
	v_add_u32_e32 v251, 0x2000, v251
	ds_read_b128 v[216:219], v251
	ds_read_b128 v[220:223], v251 offset:2304
	ds_read_b32 v192, v253
	ds_read_b32 v193, v253 offset:256
	ds_read_b32 v194, v253 offset:512
	ds_read_b32 v195, v253 offset:768
	ds_read_b32 v196, v253 offset:64
	ds_read_b32 v197, v253 offset:320
	ds_read_b32 v198, v253 offset:576
	ds_read_b32 v199, v253 offset:832
	s_waitcnt lgkmcnt(0)
	v_mfma_f32_16x16x32_bf16 v[124:127], v[192:195], v[216:219], v[124:127]
	v_mfma_f32_16x16x32_bf16 v[140:143], v[192:195], v[220:223], v[140:143]
	v_mfma_f32_16x16x32_bf16 v[128:131], v[196:199], v[216:219], v[128:131]
	v_mfma_f32_16x16x32_bf16 v[144:147], v[196:199], v[220:223], v[144:147]
	s_nop 3
	ds_read_b32 v192, v253 offset:128
	ds_read_b32 v193, v253 offset:384
	ds_read_b32 v194, v253 offset:640
	ds_read_b32 v195, v253 offset:896
	ds_read_b32 v196, v253 offset:192
	ds_read_b32 v197, v253 offset:448
	ds_read_b32 v198, v253 offset:704
	ds_read_b32 v199, v253 offset:960
	s_waitcnt lgkmcnt(0)
	v_mfma_f32_16x16x32_bf16 v[132:135], v[192:195], v[216:219], v[132:135]
	v_mfma_f32_16x16x32_bf16 v[148:151], v[192:195], v[220:223], v[148:151]
	v_mfma_f32_16x16x32_bf16 v[136:139], v[196:199], v[216:219], v[136:139]
	v_mfma_f32_16x16x32_bf16 v[152:155], v[196:199], v[220:223], v[152:155]
	s_nop 3
	ds_read_b128 v[216:219], v251 offset:4608
	ds_read_b128 v[220:223], v251 offset:6912
	ds_read_b32 v192, v253
	ds_read_b32 v193, v253 offset:256
	ds_read_b32 v194, v253 offset:512
	ds_read_b32 v195, v253 offset:768
	ds_read_b32 v196, v253 offset:64
	ds_read_b32 v197, v253 offset:320
	ds_read_b32 v198, v253 offset:576
	ds_read_b32 v199, v253 offset:832
	s_waitcnt lgkmcnt(0)
	v_mfma_f32_16x16x32_bf16 v[176:179], v[192:195], v[216:219], v[176:179]
	v_mfma_f32_16x16x32_bf16 v[234:237], v[192:195], v[220:223], v[234:237]
	v_mfma_f32_16x16x32_bf16 v[180:183], v[196:199], v[216:219], v[180:183]
	v_mfma_f32_16x16x32_bf16 v[238:241], v[196:199], v[220:223], v[238:241]
	s_nop 3
	ds_read_b32 v192, v253 offset:128
	ds_read_b32 v193, v253 offset:384
	ds_read_b32 v194, v253 offset:640
	ds_read_b32 v195, v253 offset:896
	ds_read_b32 v196, v253 offset:192
	ds_read_b32 v197, v253 offset:448
	ds_read_b32 v198, v253 offset:704
	ds_read_b32 v199, v253 offset:960
	s_waitcnt lgkmcnt(0)
	v_mfma_f32_16x16x32_bf16 v[226:229], v[192:195], v[216:219], v[226:229]
	v_mfma_f32_16x16x32_bf16 v[242:245], v[192:195], v[220:223], v[242:245]
	v_mfma_f32_16x16x32_bf16 v[230:233], v[196:199], v[216:219], v[230:233]
	v_mfma_f32_16x16x32_bf16 v[246:249], v[196:199], v[220:223], v[246:249]
	s_nop 3
	v_cndmask_b32_e64 v1, 0, 1, s[6:7]
	v_cmp_ne_u32_e32 vcc, 0, v1
	s_cmp_eq_u64 vcc, exec
	s_cselect_b64 s[28:29], -1, 0
	s_and_b64 vcc, exec, s[28:29]
	s_cbranch_vccz .LBB0_774
	s_branch .LBB0_775
